# v56 + attention: f32->bf16 RNE integer bit trick (3 VALU/value) replaced by v_cvt_pk_bf16_f32 in K staging, Q rope and output conversion (same bits; MFMA hazard distances kept with s_nop)
# speedup vs baseline: 1.0076x; 1.0076x over previous
.LBB0_565:
	s_and_b32 s60, s45, 1
	s_bfe_u32 s59, s45, 0x60001
	s_ashr_i32 s0, s45, 7
	s_lshl_b32 s1, s60, 2
	s_lshl_b32 s50, s59, 7
	s_add_i32 s16, s1, s20
	s_ashr_i32 s1, s0, 31
	s_add_i32 s51, s50, 0xffffff80
	s_lshl_b64 s[18:19], s[0:1], 13
	v_or_b32_e32 v0, s50, v112
	v_add_u32_e32 v6, s51, v119
	v_or_b32_e32 v0, s18, v0
	v_mov_b64_e32 v[4:5], s[56:57]
	v_cmp_gt_u32_e32 vcc, s37, v6
	v_mad_u64_u32 v[0:1], s[66:67], v0, s53, v[4:5]
	s_lshl_b32 s18, s16, 6
	s_lshl_b32 s17, s0, 13
	v_cndmask_b32_e32 v28, 0, v6, vcc
	v_mad_i32_i24 v1, s19, v207, v1
	s_ashr_i32 s19, s18, 31
	v_add_u32_e32 v6, s17, v28
	v_lshl_add_u64 v[0:1], s[18:19], 1, v[0:1]
	v_lshlrev_b32_e32 v152, 1, v84
	v_mad_i64_i32 v[4:5], s[18:19], v6, s53, v[4:5]
	s_lshl_b32 s8, s60, 7
	v_lshl_add_u64 v[106:107], v[0:1], 0, v[152:153]
	v_lshl_add_u64 v[4:5], v[4:5], 0, s[8:9]
	v_lshlrev_b32_e32 v152, 1, v86
	v_lshl_add_u64 v[4:5], v[4:5], 0, v[152:153]
	global_load_dwordx4 v[0:3], v[106:107], off
	global_load_dwordx4 v[8:11], v[106:107], off offset:64
	v_add_u32_e32 v12, s51, v119
	v_cmp_gt_u32_e32 vcc, s37, v12
	s_nop 1
	v_cndmask_b32_e32 v29, 0, v12, vcc
	v_add_u32_e32 v12, s17, v29
	v_mov_b64_e32 v[14:15], s[56:57]
	v_mad_i64_i32 v[14:15], s[18:19], v12, s53, v[14:15]
	v_lshl_add_u64 v[14:15], v[14:15], 0, s[8:9]
	v_lshl_add_u64 v[14:15], v[14:15], 0, v[152:153]
	global_load_dwordx4 v[44:47], v[14:15], off offset:1024
	v_add_u32_e32 v12, s51, v120
	v_cmp_gt_u32_e32 vcc, s37, v12
	s_nop 1
	v_cndmask_b32_e32 v29, 0, v12, vcc
	v_add_u32_e32 v12, s17, v29
	v_mov_b64_e32 v[14:15], s[56:57]
	v_mad_i64_i32 v[14:15], s[18:19], v12, s53, v[14:15]
	v_lshl_add_u64 v[14:15], v[14:15], 0, s[8:9]
	v_lshl_add_u64 v[14:15], v[14:15], 0, v[152:153]
	global_load_dwordx4 v[48:51], v[14:15], off offset:1024
	v_add_u32_e32 v12, s51, v121
	v_cmp_gt_u32_e32 vcc, s37, v12
	s_nop 1
	v_cndmask_b32_e32 v29, 0, v12, vcc
	v_add_u32_e32 v12, s17, v29
	v_mov_b64_e32 v[14:15], s[56:57]
	v_mad_i64_i32 v[14:15], s[18:19], v12, s53, v[14:15]
	v_lshl_add_u64 v[14:15], v[14:15], 0, s[8:9]
	v_lshl_add_u64 v[14:15], v[14:15], 0, v[152:153]
	global_load_dwordx4 v[52:55], v[14:15], off offset:1024
	v_add_u32_e32 v12, s51, v122
	v_cmp_gt_u32_e32 vcc, s37, v12
	s_nop 1
	v_cndmask_b32_e32 v29, 0, v12, vcc
	v_add_u32_e32 v12, s17, v29
	v_mov_b64_e32 v[14:15], s[56:57]
	v_mad_i64_i32 v[14:15], s[18:19], v12, s53, v[14:15]
	v_lshl_add_u64 v[14:15], v[14:15], 0, s[8:9]
	v_lshl_add_u64 v[14:15], v[14:15], 0, v[152:153]
	global_load_dwordx4 v[56:59], v[14:15], off offset:1024
	v_add_u32_e32 v12, s51, v123
	v_cmp_gt_u32_e32 vcc, s37, v12
	s_nop 1
	v_cndmask_b32_e32 v29, 0, v12, vcc
	v_add_u32_e32 v12, s17, v29
	v_mov_b64_e32 v[14:15], s[56:57]
	v_mad_i64_i32 v[14:15], s[18:19], v12, s53, v[14:15]
	v_lshl_add_u64 v[14:15], v[14:15], 0, s[8:9]
	v_lshl_add_u64 v[14:15], v[14:15], 0, v[152:153]
	global_load_dwordx4 v[60:63], v[14:15], off offset:1024
	v_add_u32_e32 v12, s51, v124
	v_cmp_gt_u32_e32 vcc, s37, v12
	s_nop 1
	v_cndmask_b32_e32 v29, 0, v12, vcc
	v_add_u32_e32 v12, s17, v29
	v_mov_b64_e32 v[14:15], s[56:57]
	v_mad_i64_i32 v[14:15], s[18:19], v12, s53, v[14:15]
	v_lshl_add_u64 v[14:15], v[14:15], 0, s[8:9]
	v_lshl_add_u64 v[14:15], v[14:15], 0, v[152:153]
	global_load_dwordx4 v[64:67], v[14:15], off offset:1024
	s_and_saveexec_b64 s[18:19], s[46:47]
	v_add_u32_e32 v12, s51, v119
	v_cmp_gt_u32_e32 vcc, s37, v12
	s_nop 1
	v_cndmask_b32_e32 v29, 0, v12, vcc
	v_lshlrev_b32_e32 v12, 4, v29
	v_ashrrev_i32_e32 v13, 31, v12
	v_lshl_add_u64 v[16:17], v[12:13], 2, s[12:13]
	global_load_dwordx4 v[68:71], v[16:17], off
	global_load_dwordx4 v[72:75], v[16:17], off offset:16
	global_load_dwordx4 v[76:79], v[16:17], off offset:32
	global_load_dwordx4 v[80:83], v[16:17], off offset:48
	v_add_u32_e32 v12, s51, v120
	v_cmp_gt_u32_e32 vcc, s37, v12
	s_nop 1
	v_cndmask_b32_e32 v29, 0, v12, vcc
	v_lshlrev_b32_e32 v12, 4, v29
	v_ashrrev_i32_e32 v13, 31, v12
	v_lshl_add_u64 v[16:17], v[12:13], 2, s[12:13]
	global_load_dwordx4 v[176:179], v[16:17], off
	global_load_dwordx4 v[180:183], v[16:17], off offset:16
	global_load_dwordx4 v[184:187], v[16:17], off offset:32
	global_load_dwordx4 v[188:191], v[16:17], off offset:48
	v_add_u32_e32 v12, s51, v121
	v_cmp_gt_u32_e32 vcc, s37, v12
	s_nop 1
	v_cndmask_b32_e32 v29, 0, v12, vcc
	v_lshlrev_b32_e32 v12, 4, v29
	v_ashrrev_i32_e32 v13, 31, v12
	v_lshl_add_u64 v[16:17], v[12:13], 2, s[12:13]
	global_load_dwordx4 v[192:195], v[16:17], off
	global_load_dwordx4 v[196:199], v[16:17], off offset:16
	global_load_dwordx4 v[144:147], v[16:17], off offset:32
	global_load_dwordx4 v[148:151], v[16:17], off offset:48
	v_add_u32_e32 v12, s51, v122
	v_cmp_gt_u32_e32 vcc, s37, v12
	s_nop 1
	v_cndmask_b32_e32 v29, 0, v12, vcc
	v_lshlrev_b32_e32 v12, 4, v29
	v_ashrrev_i32_e32 v13, 31, v12
	v_lshl_add_u64 v[16:17], v[12:13], 2, s[12:13]
	global_load_dwordx4 v[210:213], v[16:17], off
	global_load_dwordx4 v[214:217], v[16:17], off offset:16
	global_load_dwordx4 v[218:221], v[16:17], off offset:32
	global_load_dwordx4 v[224:227], v[16:17], off offset:48
	v_add_u32_e32 v12, s51, v123
	v_cmp_gt_u32_e32 vcc, s37, v12
	s_nop 1
	v_cndmask_b32_e32 v29, 0, v12, vcc
	v_lshlrev_b32_e32 v12, 4, v29
	v_ashrrev_i32_e32 v13, 31, v12
	v_lshl_add_u64 v[16:17], v[12:13], 2, s[12:13]
	global_load_dwordx4 v[228:231], v[16:17], off
	global_load_dwordx4 v[232:235], v[16:17], off offset:16
	global_load_dwordx4 v[236:239], v[16:17], off offset:32
	global_load_dwordx4 v[172:175], v[16:17], off offset:48
	s_or_b64 exec, exec, s[18:19]
	s_barrier
	s_waitcnt vmcnt(16)
	v_add_u32_e32 v12, s51, v119
	v_cmp_gt_u32_e32 vcc, s37, v12
	s_nop 1
	v_cndmask_b32_e32 v7, 0, v47, vcc
	v_cndmask_b32_e32 v6, 0, v46, vcc
	v_cndmask_b32_e32 v5, 0, v45, vcc
	v_cndmask_b32_e32 v4, 0, v44, vcc
	v_lshlrev_b32_e32 v13, 16, v5
	v_lshlrev_b32_e32 v12, 16, v4
	v_and_b32_e32 v15, 0xffff0000, v5
	v_and_b32_e32 v14, 0xffff0000, v4
	v_and_b32_e32 v17, 0xffff0000, v6
	v_lshlrev_b32_e32 v16, 16, v6
	v_and_b32_e32 v19, 0xffff0000, v7
	v_lshlrev_b32_e32 v18, 16, v7
	ds_bpermute_b32 v26, v113, v12
	ds_bpermute_b32 v24, v113, v14
	ds_bpermute_b32 v27, v113, v13
	ds_bpermute_b32 v25, v113, v15
	ds_bpermute_b32 v22, v113, v16
	ds_bpermute_b32 v23, v113, v17
	ds_bpermute_b32 v20, v113, v18
	ds_bpermute_b32 v21, v113, v19
	s_and_saveexec_b64 s[18:19], s[46:47]
	s_waitcnt lgkmcnt(4)
	v_pk_mul_f32 v[24:25], v[88:89], v[24:25]
	s_waitcnt lgkmcnt(2)
	v_pk_mul_f32 v[22:23], v[88:89], v[22:23]
	s_waitcnt lgkmcnt(0)
	v_pk_mul_f32 v[20:21], v[88:89], v[20:21]
	v_pk_mul_f32 v[26:27], v[88:89], v[26:27]
	v_mov_b32_e32 v40, v68
	v_mov_b32_e32 v41, v70
	v_mov_b32_e32 v42, v76
	v_mov_b32_e32 v43, v78
	v_mov_b32_e32 v30, v77
	v_mov_b32_e32 v31, v79
	v_mov_b32_e32 v6, v69
	v_mov_b32_e32 v7, v71
	v_pk_mul_f32 v[4:5], v[22:23], v[80:81]
	v_pk_mul_f32 v[20:21], v[20:21], v[82:83]
	v_pk_mul_f32 v[24:25], v[24:25], v[30:31]
	v_pk_mul_f32 v[22:23], v[26:27], v[42:43]
	v_pk_fma_f32 v[4:5], v[72:73], v[16:17], v[4:5]
	v_pk_fma_f32 v[16:17], v[74:75], v[18:19], v[20:21]
	v_pk_fma_f32 v[6:7], v[6:7], v[14:15], v[24:25]
	v_pk_fma_f32 v[12:13], v[40:41], v[12:13], v[22:23]
	v_cvt_pk_bf16_f32 v14, v4, v5
	v_cvt_pk_bf16_f32 v5, v13, v7
	v_cvt_pk_bf16_f32 v4, v12, v6
	v_cvt_pk_bf16_f32 v7, v16, v17
	v_mov_b32_e32 v6, v14
	s_or_b64 exec, exec, s[18:19]
	ds_write_b128 v85, v[4:7]
	s_and_saveexec_b64 s[18:19], s[46:47]
	v_add_u32_e32 v12, s51, v124
	v_cmp_gt_u32_e32 vcc, s37, v12
	s_nop 1
	v_cndmask_b32_e32 v29, 0, v12, vcc
	v_lshlrev_b32_e32 v12, 4, v29
	v_ashrrev_i32_e32 v13, 31, v12
	v_lshl_add_u64 v[16:17], v[12:13], 2, s[12:13]
	global_load_dwordx4 v[68:71], v[16:17], off
	global_load_dwordx4 v[72:75], v[16:17], off offset:16
	global_load_dwordx4 v[76:79], v[16:17], off offset:32
	global_load_dwordx4 v[80:83], v[16:17], off offset:48
	s_or_b64 exec, exec, s[18:19]
	s_waitcnt vmcnt(16)
	v_add_u32_e32 v12, s51, v120
	v_cmp_gt_u32_e32 vcc, s37, v12
	s_nop 1
	v_cndmask_b32_e32 v7, 0, v51, vcc
	v_cndmask_b32_e32 v6, 0, v50, vcc
	v_cndmask_b32_e32 v5, 0, v49, vcc
	v_cndmask_b32_e32 v4, 0, v48, vcc
	v_lshlrev_b32_e32 v13, 16, v5
	v_lshlrev_b32_e32 v12, 16, v4
	v_and_b32_e32 v15, 0xffff0000, v5
	v_and_b32_e32 v14, 0xffff0000, v4
	v_and_b32_e32 v17, 0xffff0000, v6
	v_lshlrev_b32_e32 v16, 16, v6
	v_and_b32_e32 v19, 0xffff0000, v7
	v_lshlrev_b32_e32 v18, 16, v7
	ds_bpermute_b32 v26, v113, v12
	ds_bpermute_b32 v24, v113, v14
	ds_bpermute_b32 v27, v113, v13
	ds_bpermute_b32 v25, v113, v15
	ds_bpermute_b32 v22, v113, v16
	ds_bpermute_b32 v23, v113, v17
	ds_bpermute_b32 v20, v113, v18
	ds_bpermute_b32 v21, v113, v19
	s_and_saveexec_b64 s[18:19], s[46:47]
	s_waitcnt lgkmcnt(4)
	v_pk_mul_f32 v[24:25], v[88:89], v[24:25]
	s_waitcnt lgkmcnt(2)
	v_pk_mul_f32 v[22:23], v[88:89], v[22:23]
	s_waitcnt lgkmcnt(0)
	v_pk_mul_f32 v[20:21], v[88:89], v[20:21]
	v_pk_mul_f32 v[26:27], v[88:89], v[26:27]
	v_mov_b32_e32 v40, v176
	v_mov_b32_e32 v41, v178
	v_mov_b32_e32 v42, v184
	v_mov_b32_e32 v43, v186
	v_mov_b32_e32 v30, v185
	v_mov_b32_e32 v31, v187
	v_mov_b32_e32 v6, v177
	v_mov_b32_e32 v7, v179
	v_pk_mul_f32 v[4:5], v[22:23], v[188:189]
	v_pk_mul_f32 v[20:21], v[20:21], v[190:191]
	v_pk_mul_f32 v[24:25], v[24:25], v[30:31]
	v_pk_mul_f32 v[22:23], v[26:27], v[42:43]
	v_pk_fma_f32 v[4:5], v[180:181], v[16:17], v[4:5]
	v_pk_fma_f32 v[16:17], v[182:183], v[18:19], v[20:21]
	v_pk_fma_f32 v[6:7], v[6:7], v[14:15], v[24:25]
	v_pk_fma_f32 v[12:13], v[40:41], v[12:13], v[22:23]
	v_cvt_pk_bf16_f32 v14, v4, v5
	v_cvt_pk_bf16_f32 v5, v13, v7
	v_cvt_pk_bf16_f32 v4, v12, v6
	v_cvt_pk_bf16_f32 v7, v16, v17
	v_mov_b32_e32 v6, v14
	s_or_b64 exec, exec, s[18:19]
	ds_write_b128 v138, v[4:7]
	v_add_u32_e32 v12, s51, v125
	v_cmp_gt_u32_e32 vcc, s37, v12
	s_nop 1
	v_cndmask_b32_e32 v29, 0, v12, vcc
	v_add_u32_e32 v12, s17, v29
	v_mov_b64_e32 v[14:15], s[56:57]
	v_mad_i64_i32 v[14:15], s[18:19], v12, s53, v[14:15]
	v_lshl_add_u64 v[14:15], v[14:15], 0, s[8:9]
	v_lshl_add_u64 v[14:15], v[92:93], 1, v[14:15]
	global_load_dwordx4 v[44:47], v[14:15], off offset:1280
	v_add_u32_e32 v12, s51, v127
	v_cmp_gt_u32_e32 vcc, s37, v12
	s_nop 1
	v_cndmask_b32_e32 v29, 0, v12, vcc
	v_add_u32_e32 v12, s17, v29
	v_mov_b64_e32 v[14:15], s[56:57]
	v_mad_i64_i32 v[14:15], s[18:19], v12, s53, v[14:15]
	v_lshl_add_u64 v[14:15], v[14:15], 0, s[8:9]
	v_lshl_add_u64 v[14:15], v[94:95], 1, v[14:15]
	global_load_dwordx4 v[48:51], v[14:15], off offset:1280
	v_add_u32_e32 v12, s51, v129
	v_cmp_gt_u32_e32 vcc, s37, v12
	s_nop 1
	v_cndmask_b32_e32 v29, 0, v12, vcc
	v_add_u32_e32 v12, s17, v29
	v_mov_b64_e32 v[14:15], s[56:57]
	v_mad_i64_i32 v[14:15], s[18:19], v12, s53, v[14:15]
	v_lshl_add_u64 v[14:15], v[14:15], 0, s[8:9]
	v_lshl_add_u64 v[14:15], v[96:97], 1, v[14:15]
	global_load_dwordx4 v[176:179], v[14:15], off offset:1280
	v_add_u32_e32 v12, s51, v131
	v_cmp_gt_u32_e32 vcc, s37, v12
	s_nop 1
	v_cndmask_b32_e32 v29, 0, v12, vcc
	v_add_u32_e32 v12, s17, v29
	v_mov_b64_e32 v[14:15], s[56:57]
	v_mad_i64_i32 v[14:15], s[18:19], v12, s53, v[14:15]
	v_lshl_add_u64 v[14:15], v[14:15], 0, s[8:9]
	v_lshl_add_u64 v[14:15], v[98:99], 1, v[14:15]
	global_load_dwordx4 v[180:183], v[14:15], off offset:1280
	v_add_u32_e32 v12, s51, v133
	v_cmp_gt_u32_e32 vcc, s37, v12
	s_nop 1
	v_cndmask_b32_e32 v29, 0, v12, vcc
	v_add_u32_e32 v12, s17, v29
	v_mov_b64_e32 v[14:15], s[56:57]
	v_mad_i64_i32 v[14:15], s[18:19], v12, s53, v[14:15]
	v_lshl_add_u64 v[14:15], v[14:15], 0, s[8:9]
	v_lshl_add_u64 v[14:15], v[100:101], 1, v[14:15]
	global_load_dwordx4 v[184:187], v[14:15], off offset:1280
	v_add_u32_e32 v12, s51, v135
	v_cmp_gt_u32_e32 vcc, s37, v12
	s_nop 1
	v_cndmask_b32_e32 v29, 0, v12, vcc
	v_add_u32_e32 v12, s17, v29
	v_mov_b64_e32 v[14:15], s[56:57]
	v_mad_i64_i32 v[14:15], s[18:19], v12, s53, v[14:15]
	v_lshl_add_u64 v[14:15], v[14:15], 0, s[8:9]
	v_lshl_add_u64 v[14:15], v[102:103], 1, v[14:15]
	global_load_dwordx4 v[188:191], v[14:15], off offset:1280
	s_waitcnt vmcnt(18)
	v_add_u32_e32 v12, s51, v121
	v_cmp_gt_u32_e32 vcc, s37, v12
	s_nop 1
	v_cndmask_b32_e32 v7, 0, v55, vcc
	v_cndmask_b32_e32 v6, 0, v54, vcc
	v_cndmask_b32_e32 v5, 0, v53, vcc
	v_cndmask_b32_e32 v4, 0, v52, vcc
	v_lshlrev_b32_e32 v13, 16, v5
	v_lshlrev_b32_e32 v12, 16, v4
	v_and_b32_e32 v15, 0xffff0000, v5
	v_and_b32_e32 v14, 0xffff0000, v4
	v_and_b32_e32 v17, 0xffff0000, v6
	v_lshlrev_b32_e32 v16, 16, v6
	v_and_b32_e32 v19, 0xffff0000, v7
	v_lshlrev_b32_e32 v18, 16, v7
	ds_bpermute_b32 v26, v113, v12
	ds_bpermute_b32 v24, v113, v14
	ds_bpermute_b32 v27, v113, v13
	ds_bpermute_b32 v25, v113, v15
	ds_bpermute_b32 v22, v113, v16
	ds_bpermute_b32 v23, v113, v17
	ds_bpermute_b32 v20, v113, v18
	ds_bpermute_b32 v21, v113, v19
	s_and_saveexec_b64 s[18:19], s[46:47]
	s_waitcnt lgkmcnt(4)
	v_pk_mul_f32 v[24:25], v[88:89], v[24:25]
	s_waitcnt lgkmcnt(2)
	v_pk_mul_f32 v[22:23], v[88:89], v[22:23]
	s_waitcnt lgkmcnt(0)
	v_pk_mul_f32 v[20:21], v[88:89], v[20:21]
	v_pk_mul_f32 v[26:27], v[88:89], v[26:27]
	v_mov_b32_e32 v40, v192
	v_mov_b32_e32 v41, v194
	v_mov_b32_e32 v42, v144
	v_mov_b32_e32 v43, v146
	v_mov_b32_e32 v30, v145
	v_mov_b32_e32 v31, v147
	v_mov_b32_e32 v6, v193
	v_mov_b32_e32 v7, v195
	v_pk_mul_f32 v[4:5], v[22:23], v[148:149]
	v_pk_mul_f32 v[20:21], v[20:21], v[150:151]
	v_pk_mul_f32 v[24:25], v[24:25], v[30:31]
	v_pk_mul_f32 v[22:23], v[26:27], v[42:43]
	v_pk_fma_f32 v[4:5], v[196:197], v[16:17], v[4:5]
	v_pk_fma_f32 v[16:17], v[198:199], v[18:19], v[20:21]
	v_pk_fma_f32 v[6:7], v[6:7], v[14:15], v[24:25]
	v_pk_fma_f32 v[12:13], v[40:41], v[12:13], v[22:23]
	v_cvt_pk_bf16_f32 v14, v4, v5
	v_cvt_pk_bf16_f32 v5, v13, v7
	v_cvt_pk_bf16_f32 v4, v12, v6
	v_cvt_pk_bf16_f32 v7, v16, v17
	v_mov_b32_e32 v6, v14
	s_or_b64 exec, exec, s[18:19]
	ds_write_b128 v139, v[4:7]
	s_waitcnt vmcnt(14)
	v_add_u32_e32 v12, s51, v122
	v_cmp_gt_u32_e32 vcc, s37, v12
	s_nop 1
	v_cndmask_b32_e32 v7, 0, v59, vcc
	v_cndmask_b32_e32 v6, 0, v58, vcc
	v_cndmask_b32_e32 v5, 0, v57, vcc
	v_cndmask_b32_e32 v4, 0, v56, vcc
	v_lshlrev_b32_e32 v13, 16, v5
	v_lshlrev_b32_e32 v12, 16, v4
	v_and_b32_e32 v15, 0xffff0000, v5
	v_and_b32_e32 v14, 0xffff0000, v4
	v_and_b32_e32 v17, 0xffff0000, v6
	v_lshlrev_b32_e32 v16, 16, v6
	v_and_b32_e32 v19, 0xffff0000, v7
	v_lshlrev_b32_e32 v18, 16, v7
	ds_bpermute_b32 v26, v113, v12
	ds_bpermute_b32 v24, v113, v14
	ds_bpermute_b32 v27, v113, v13
	ds_bpermute_b32 v25, v113, v15
	ds_bpermute_b32 v22, v113, v16
	ds_bpermute_b32 v23, v113, v17
	ds_bpermute_b32 v20, v113, v18
	ds_bpermute_b32 v21, v113, v19
	s_and_saveexec_b64 s[18:19], s[46:47]
	s_waitcnt lgkmcnt(4)
	v_pk_mul_f32 v[24:25], v[88:89], v[24:25]
	s_waitcnt lgkmcnt(2)
	v_pk_mul_f32 v[22:23], v[88:89], v[22:23]
	s_waitcnt lgkmcnt(0)
	v_pk_mul_f32 v[20:21], v[88:89], v[20:21]
	v_pk_mul_f32 v[26:27], v[88:89], v[26:27]
	v_mov_b32_e32 v40, v210
	v_mov_b32_e32 v41, v212
	v_mov_b32_e32 v42, v218
	v_mov_b32_e32 v43, v220
	v_mov_b32_e32 v30, v219
	v_mov_b32_e32 v31, v221
	v_mov_b32_e32 v6, v211
	v_mov_b32_e32 v7, v213
	v_pk_mul_f32 v[4:5], v[22:23], v[224:225]
	v_pk_mul_f32 v[20:21], v[20:21], v[226:227]
	v_pk_mul_f32 v[24:25], v[24:25], v[30:31]
	v_pk_mul_f32 v[22:23], v[26:27], v[42:43]
	v_pk_fma_f32 v[4:5], v[214:215], v[16:17], v[4:5]
	v_pk_fma_f32 v[16:17], v[216:217], v[18:19], v[20:21]
	v_pk_fma_f32 v[6:7], v[6:7], v[14:15], v[24:25]
	v_pk_fma_f32 v[12:13], v[40:41], v[12:13], v[22:23]
	v_cvt_pk_bf16_f32 v14, v4, v5
	v_cvt_pk_bf16_f32 v5, v13, v7
	v_cvt_pk_bf16_f32 v4, v12, v6
	v_cvt_pk_bf16_f32 v7, v16, v17
	v_mov_b32_e32 v6, v14
	s_or_b64 exec, exec, s[18:19]
	ds_write_b128 v140, v[4:7]
	s_waitcnt vmcnt(10)
	v_add_u32_e32 v12, s51, v123
	v_cmp_gt_u32_e32 vcc, s37, v12
	s_nop 1
	v_cndmask_b32_e32 v7, 0, v63, vcc
	v_cndmask_b32_e32 v6, 0, v62, vcc
	v_cndmask_b32_e32 v5, 0, v61, vcc
	v_cndmask_b32_e32 v4, 0, v60, vcc
	v_lshlrev_b32_e32 v13, 16, v5
	v_lshlrev_b32_e32 v12, 16, v4
	v_and_b32_e32 v15, 0xffff0000, v5
	v_and_b32_e32 v14, 0xffff0000, v4
	v_and_b32_e32 v17, 0xffff0000, v6
	v_lshlrev_b32_e32 v16, 16, v6
	v_and_b32_e32 v19, 0xffff0000, v7
	v_lshlrev_b32_e32 v18, 16, v7
	ds_bpermute_b32 v26, v113, v12
	ds_bpermute_b32 v24, v113, v14
	ds_bpermute_b32 v27, v113, v13
	ds_bpermute_b32 v25, v113, v15
	ds_bpermute_b32 v22, v113, v16
	ds_bpermute_b32 v23, v113, v17
	ds_bpermute_b32 v20, v113, v18
	ds_bpermute_b32 v21, v113, v19
	s_and_saveexec_b64 s[18:19], s[46:47]
	s_waitcnt lgkmcnt(4)
	v_pk_mul_f32 v[24:25], v[88:89], v[24:25]
	s_waitcnt lgkmcnt(2)
	v_pk_mul_f32 v[22:23], v[88:89], v[22:23]
	s_waitcnt lgkmcnt(0)
	v_pk_mul_f32 v[20:21], v[88:89], v[20:21]
	v_pk_mul_f32 v[26:27], v[88:89], v[26:27]
	v_mov_b32_e32 v40, v228
	v_mov_b32_e32 v41, v230
	v_mov_b32_e32 v42, v236
	v_mov_b32_e32 v43, v238
	v_mov_b32_e32 v30, v237
	v_mov_b32_e32 v31, v239
	v_mov_b32_e32 v6, v229
	v_mov_b32_e32 v7, v231
	v_pk_mul_f32 v[4:5], v[22:23], v[172:173]
	v_pk_mul_f32 v[20:21], v[20:21], v[174:175]
	v_pk_mul_f32 v[24:25], v[24:25], v[30:31]
	v_pk_mul_f32 v[22:23], v[26:27], v[42:43]
	v_pk_fma_f32 v[4:5], v[232:233], v[16:17], v[4:5]
	v_pk_fma_f32 v[16:17], v[234:235], v[18:19], v[20:21]
	v_pk_fma_f32 v[6:7], v[6:7], v[14:15], v[24:25]
	v_pk_fma_f32 v[12:13], v[40:41], v[12:13], v[22:23]
	v_cvt_pk_bf16_f32 v14, v4, v5
	v_cvt_pk_bf16_f32 v5, v13, v7
	v_cvt_pk_bf16_f32 v4, v12, v6
	v_cvt_pk_bf16_f32 v7, v16, v17
	v_mov_b32_e32 v6, v14
	s_or_b64 exec, exec, s[18:19]
	ds_write_b128 v141, v[4:7]
	s_waitcnt vmcnt(6)
	v_add_u32_e32 v12, s51, v124
	v_cmp_gt_u32_e32 vcc, s37, v12
	s_nop 1
	v_cndmask_b32_e32 v7, 0, v67, vcc
	v_cndmask_b32_e32 v6, 0, v66, vcc
	v_cndmask_b32_e32 v5, 0, v65, vcc
	v_cndmask_b32_e32 v4, 0, v64, vcc
	v_lshlrev_b32_e32 v13, 16, v5
	v_lshlrev_b32_e32 v12, 16, v4
	v_and_b32_e32 v15, 0xffff0000, v5
	v_and_b32_e32 v14, 0xffff0000, v4
	v_and_b32_e32 v17, 0xffff0000, v6
	v_lshlrev_b32_e32 v16, 16, v6
	v_and_b32_e32 v19, 0xffff0000, v7
	v_lshlrev_b32_e32 v18, 16, v7
	ds_bpermute_b32 v26, v113, v12
	ds_bpermute_b32 v24, v113, v14
	ds_bpermute_b32 v27, v113, v13
	ds_bpermute_b32 v25, v113, v15
	ds_bpermute_b32 v22, v113, v16
	ds_bpermute_b32 v23, v113, v17
	ds_bpermute_b32 v20, v113, v18
	ds_bpermute_b32 v21, v113, v19
	s_and_saveexec_b64 s[18:19], s[46:47]
	s_waitcnt lgkmcnt(4)
	v_pk_mul_f32 v[24:25], v[88:89], v[24:25]
	s_waitcnt lgkmcnt(2)
	v_pk_mul_f32 v[22:23], v[88:89], v[22:23]
	s_waitcnt lgkmcnt(0)
	v_pk_mul_f32 v[20:21], v[88:89], v[20:21]
	v_pk_mul_f32 v[26:27], v[88:89], v[26:27]
	v_mov_b32_e32 v40, v68
	v_mov_b32_e32 v41, v70
	v_mov_b32_e32 v42, v76
	v_mov_b32_e32 v43, v78
	v_mov_b32_e32 v30, v77
	v_mov_b32_e32 v31, v79
	v_mov_b32_e32 v6, v69
	v_mov_b32_e32 v7, v71
	v_pk_mul_f32 v[4:5], v[22:23], v[80:81]
	v_pk_mul_f32 v[20:21], v[20:21], v[82:83]
	v_pk_mul_f32 v[24:25], v[24:25], v[30:31]
	v_pk_mul_f32 v[22:23], v[26:27], v[42:43]
	v_pk_fma_f32 v[4:5], v[72:73], v[16:17], v[4:5]
	v_pk_fma_f32 v[16:17], v[74:75], v[18:19], v[20:21]
	v_pk_fma_f32 v[6:7], v[6:7], v[14:15], v[24:25]
	v_pk_fma_f32 v[12:13], v[40:41], v[12:13], v[22:23]
	v_cvt_pk_bf16_f32 v14, v4, v5
	v_cvt_pk_bf16_f32 v5, v13, v7
	v_cvt_pk_bf16_f32 v4, v12, v6
	v_cvt_pk_bf16_f32 v7, v16, v17
	v_mov_b32_e32 v6, v14
	s_or_b64 exec, exec, s[18:19]
	ds_write_b128 v142, v[4:7]
	s_waitcnt vmcnt(5)
	v_add_u32_e32 v12, s51, v125
	v_cmp_gt_u32_e32 vcc, s37, v12
	s_nop 1
	v_cndmask_b32_e32 v4, 0, v44, vcc
	v_cndmask_b32_e32 v5, 0, v45, vcc
	v_cndmask_b32_e32 v6, 0, v46, vcc
	v_cndmask_b32_e32 v7, 0, v47, vcc
	ds_write_b16 v126, v4 offset:55296
	ds_write_b16_d16_hi v126, v4 offset:56080
	ds_write_b16 v126, v5 offset:56864
	ds_write_b16_d16_hi v126, v5 offset:57648
	ds_write_b16 v126, v6 offset:58432
	ds_write_b16_d16_hi v126, v6 offset:59216
	ds_write_b16 v126, v7 offset:60000
	ds_write_b16_d16_hi v126, v7 offset:60784
	s_waitcnt vmcnt(4)
	v_add_u32_e32 v12, s51, v127
	v_cmp_gt_u32_e32 vcc, s37, v12
	s_nop 1
	v_cndmask_b32_e32 v4, 0, v48, vcc
	v_cndmask_b32_e32 v5, 0, v49, vcc
	v_cndmask_b32_e32 v6, 0, v50, vcc
	v_cndmask_b32_e32 v7, 0, v51, vcc
	ds_write_b16 v128, v4 offset:56320
	ds_write_b16_d16_hi v128, v4 offset:57104
	ds_write_b16 v128, v5 offset:57888
	ds_write_b16_d16_hi v128, v5 offset:58672
	ds_write_b16 v128, v6 offset:59456
	ds_write_b16_d16_hi v128, v6 offset:60240
	ds_write_b16 v128, v7 offset:61024
	ds_write_b16_d16_hi v128, v7 offset:61808
	s_waitcnt vmcnt(3)
	v_add_u32_e32 v12, s51, v129
	v_cmp_gt_u32_e32 vcc, s37, v12
	s_nop 1
	v_cndmask_b32_e32 v4, 0, v176, vcc
	v_cndmask_b32_e32 v5, 0, v177, vcc
	v_cndmask_b32_e32 v6, 0, v178, vcc
	v_cndmask_b32_e32 v7, 0, v179, vcc
	ds_write_b16 v130, v4 offset:57344
	ds_write_b16_d16_hi v130, v4 offset:58128
	ds_write_b16 v130, v5 offset:58912
	ds_write_b16_d16_hi v130, v5 offset:59696
	ds_write_b16 v130, v6 offset:60480
	ds_write_b16_d16_hi v130, v6 offset:61264
	ds_write_b16 v130, v7 offset:62048
	ds_write_b16_d16_hi v130, v7 offset:62832
	s_waitcnt vmcnt(2)
	v_add_u32_e32 v12, s51, v131
	v_cmp_gt_u32_e32 vcc, s37, v12
	s_nop 1
	v_cndmask_b32_e32 v4, 0, v180, vcc
	v_cndmask_b32_e32 v5, 0, v181, vcc
	v_cndmask_b32_e32 v6, 0, v182, vcc
	v_cndmask_b32_e32 v7, 0, v183, vcc
	ds_write_b16 v132, v4 offset:58368
	ds_write_b16_d16_hi v132, v4 offset:59152
	ds_write_b16 v132, v5 offset:59936
	ds_write_b16_d16_hi v132, v5 offset:60720
	ds_write_b16 v132, v6 offset:61504
	ds_write_b16_d16_hi v132, v6 offset:62288
	ds_write_b16 v132, v7 offset:63072
	ds_write_b16_d16_hi v132, v7 offset:63856
	s_waitcnt vmcnt(1)
	v_add_u32_e32 v12, s51, v133
	v_cmp_gt_u32_e32 vcc, s37, v12
	s_nop 1
	v_cndmask_b32_e32 v4, 0, v184, vcc
	v_cndmask_b32_e32 v5, 0, v185, vcc
	v_cndmask_b32_e32 v6, 0, v186, vcc
	v_cndmask_b32_e32 v7, 0, v187, vcc
	ds_write_b16 v134, v4 offset:59392
	ds_write_b16_d16_hi v134, v4 offset:60176
	ds_write_b16 v134, v5 offset:60960
	ds_write_b16_d16_hi v134, v5 offset:61744
	ds_write_b16 v134, v6 offset:62528
	ds_write_b16_d16_hi v134, v6 offset:63312
	ds_write_b16 v134, v7 offset:64096
	ds_write_b16_d16_hi v134, v7 offset:64880
	s_waitcnt vmcnt(0)
	v_add_u32_e32 v12, s51, v135
	v_cmp_gt_u32_e32 vcc, s37, v12
	s_nop 1
	v_cndmask_b32_e32 v4, 0, v188, vcc
	v_cndmask_b32_e32 v5, 0, v189, vcc
	v_cndmask_b32_e32 v6, 0, v190, vcc
	v_cndmask_b32_e32 v7, 0, v191, vcc
	ds_write_b16 v136, v4 offset:60416
	ds_write_b16_d16_hi v136, v4 offset:61200
	ds_write_b16 v136, v5 offset:61984
	ds_write_b16_d16_hi v136, v5 offset:62768
	ds_write_b16 v136, v6 offset:63552
	ds_write_b16_d16_hi v136, v6 offset:64336
	ds_write_b16 v136, v7 offset:65120
	ds_write_b16_d16_hi v137, v7 offset:5488
	s_lshr_b32 s18, s45, 1
	s_and_b32 s18, s18, 63
	v_lshl_or_b32 v12, s18, 7, v112
	v_lshlrev_b32_e32 v152, 6, v12
	v_lshl_add_u64 v[108:109], s[12:13], 0, v[152:153]
	v_lshlrev_b32_e32 v152, 10, v12
	v_cndmask_b32_e64 v12, 0, 1, s[10:11]
	s_nop 1
	v_readfirstlane_b32 s18, v12
	s_nop 1
	s_lshl_b32 s18, s18, 8
	s_add_i32 s18, s44, s18
	s_ashr_i32 s19, s18, 31
	s_lshl_b64 s[18:19], s[18:19], 1
	s_ashr_i32 s17, s16, 31
	s_lshl_b64 s[16:17], s[16:17], 2
	v_readlane_b32 s8, v254, 0
	s_nop 1
	s_add_u32 s16, s8, s16
	v_readlane_b32 s8, v254, 1
	s_nop 1
	s_addc_u32 s17, s8, s17
	s_sub_i32 s60, 0x80, s50
	s_sub_i32 s61, 0x2080, s50
	s_lshl_b64 s[0:1], s[0:1], 23
	s_add_u32 s0, s18, s0
	s_addc_u32 s1, s19, s1
	s_mov_b32 s18, 0xd000
	s_mov_b32 s19, s21
	s_waitcnt lgkmcnt(0)
	s_barrier
	s_and_saveexec_b64 s[50:51], s[48:49]
	global_load_dwordx4 v[176:179], v[108:109], off
	global_load_dwordx4 v[180:183], v[108:109], off offset:32
	global_load_dwordx4 v[184:187], v[108:109], off offset:48
	global_load_dwordx4 v[188:191], v[108:109], off offset:16
	s_or_b64 exec, exec, s[50:51]
	global_load_dword v4, v153, s[16:17]
	s_mov_b64 s[16:17], 0
	s_waitcnt vmcnt(0)
	v_mul_f32_e32 v143, 0x3fb8aa3b, v4
	v_lshl_add_u64 v[4:5], s[0:1], 0, v[152:153]
	v_lshl_add_u64 v[110:111], v[104:105], 0, v[4:5]
	s_branch .LBB0_579
.LBB0_578:
	v_or_b32_e32 v16, 0x100, v80
	v_cmp_le_u32_e32 vcc, v80, v149
	v_cmp_gt_u32_e64 s[0:1], s61, v16
	s_and_b64 vcc, vcc, s[0:1]
	v_mul_f32_e32 v12, 0x3e38aa3b, v12
	v_or_b32_e32 v16, 0x104, v80
	v_cndmask_b32_e32 v12, v208, v12, vcc
	v_cmp_le_u32_e32 vcc, v16, v51
	v_cmp_gt_u32_e64 s[0:1], s61, v16
	s_and_b64 vcc, vcc, s[0:1]
	v_mul_f32_e32 v8, 0x3e38aa3b, v8
	v_or_b32_e32 v17, 0x101, v80
	v_cndmask_b32_e32 v8, v208, v8, vcc
	v_cmp_le_u32_e32 vcc, v17, v51
	v_cmp_gt_u32_e64 s[0:1], s61, v17
	s_and_b64 vcc, vcc, s[0:1]
	v_mul_f32_e32 v13, 0x3e38aa3b, v13
	v_or_b32_e32 v17, 0x105, v80
	v_cndmask_b32_e32 v13, v208, v13, vcc
	v_cmp_le_u32_e32 vcc, v17, v51
	v_cmp_gt_u32_e64 s[0:1], s61, v17
	s_and_b64 vcc, vcc, s[0:1]
	v_mul_f32_e32 v9, 0x3e38aa3b, v9
	v_cndmask_b32_e32 v149, v208, v9, vcc
	v_max_f32_e32 v16, v12, v8
	v_max_f32_e32 v9, v13, v149
	v_max3_f32 v9, v151, v16, v9
	v_or_b32_e32 v16, 0x102, v80
	v_cmp_le_u32_e32 vcc, v16, v51
	v_cmp_gt_u32_e64 s[0:1], s61, v16
	s_and_b64 vcc, vcc, s[0:1]
	v_mul_f32_e32 v14, 0x3e38aa3b, v14
	v_or_b32_e32 v16, 0x106, v80
	v_cndmask_b32_e32 v14, v208, v14, vcc
	v_cmp_le_u32_e32 vcc, v16, v51
	v_cmp_gt_u32_e64 s[0:1], s61, v16
	s_and_b64 vcc, vcc, s[0:1]
	v_mul_f32_e32 v10, 0x3e38aa3b, v10
	v_or_b32_e32 v16, 0x103, v80
	v_cndmask_b32_e32 v151, v208, v10, vcc
	v_cmp_le_u32_e32 vcc, v16, v51
	v_cmp_gt_u32_e64 s[0:1], s61, v16
	s_and_b64 vcc, vcc, s[0:1]
	v_mul_f32_e32 v15, 0x3e38aa3b, v15
	v_cndmask_b32_e32 v152, v208, v15, vcc
	v_or_b32_e32 v15, 0x107, v80
	v_cmp_le_u32_e32 vcc, v15, v51
	v_cmp_gt_u32_e64 s[0:1], s61, v15
	s_and_b64 vcc, vcc, s[0:1]
	v_mul_f32_e32 v11, 0x3e38aa3b, v11
	v_cndmask_b32_e32 v173, v208, v11, vcc
	v_max_f32_e32 v10, v14, v151
	v_max_f32_e32 v11, v152, v173
	v_max3_f32 v9, v9, v10, v11
	ds_bpermute_b32 v10, v114, v9
	s_waitcnt lgkmcnt(0)
	v_max_f32_e32 v10, v10, v10
	v_max_f32_e32 v9, v9, v10
	ds_bpermute_b32 v10, v117, v9
	s_waitcnt lgkmcnt(0)
	v_max_f32_e32 v10, v10, v10
	v_max_f32_e32 v172, v9, v10
	v_sub_f32_e32 v9, v81, v172
	v_exp_f32_e32 v81, v9
	v_sub_f32_e32 v9, v82, v172
	v_sub_f32_e32 v10, v83, v172
	v_exp_f32_e32 v82, v9
	v_exp_f32_e32 v83, v10
	v_sub_f32_e32 v10, v144, v172
	v_exp_f32_e32 v144, v10
	v_add_f32_e32 v9, v81, v82
	v_add_f32_e32 v9, 0, v9
	v_sub_f32_e32 v8, v8, v172
	v_add_f32_e32 v10, v83, v144
	v_add_f32_e32 v9, v10, v9
	v_sub_f32_e32 v10, v145, v172
	v_exp_f32_e32 v145, v10
	v_sub_f32_e32 v10, v146, v172
	v_exp_f32_e32 v146, v10
	s_nop 0
	v_add_f32_e32 v10, v145, v146
	v_add_f32_e32 v9, v10, v9
	v_sub_f32_e32 v10, v147, v172
	v_exp_f32_e32 v147, v10
	v_sub_f32_e32 v10, v148, v172
	v_exp_f32_e32 v148, v10
	s_nop 0
	v_add_f32_e32 v10, v147, v148
	v_add_f32_e32 v9, v10, v9
	v_sub_f32_e32 v10, v74, v172
	v_exp_f32_e32 v51, v10
	v_sub_f32_e32 v10, v72, v172
	v_exp_f32_e32 v72, v10
	s_nop 0
	v_add_f32_e32 v10, v51, v72
	v_add_f32_e32 v9, v10, v9
	v_sub_f32_e32 v10, v75, v172
	v_exp_f32_e32 v74, v10
	v_sub_f32_e32 v10, v73, v172
	v_exp_f32_e32 v73, v10
	s_nop 0
	v_add_f32_e32 v10, v74, v73
	v_add_f32_e32 v9, v10, v9
	v_sub_f32_e32 v10, v78, v172
	v_exp_f32_e32 v75, v10
	v_sub_f32_e32 v10, v76, v172
	v_exp_f32_e32 v76, v10
	s_nop 0
	v_add_f32_e32 v10, v75, v76
	v_add_f32_e32 v9, v10, v9
	v_sub_f32_e32 v10, v79, v172
	v_exp_f32_e32 v78, v10
	v_sub_f32_e32 v10, v77, v172
	v_exp_f32_e32 v79, v10
	s_nop 0
	v_add_f32_e32 v10, v78, v79
	v_add_f32_e32 v9, v10, v9
	v_sub_f32_e32 v10, v66, v172
	v_exp_f32_e32 v66, v10
	v_sub_f32_e32 v10, v64, v172
	v_exp_f32_e32 v64, v10
	s_nop 0
	v_add_f32_e32 v10, v66, v64
	v_add_f32_e32 v9, v10, v9
	v_sub_f32_e32 v10, v67, v172
	v_exp_f32_e32 v67, v10
	v_sub_f32_e32 v10, v65, v172
	v_exp_f32_e32 v65, v10
	s_nop 0
	v_add_f32_e32 v10, v67, v65
	v_add_f32_e32 v9, v10, v9
	v_sub_f32_e32 v10, v70, v172
	v_exp_f32_e32 v70, v10
	v_sub_f32_e32 v10, v68, v172
	v_exp_f32_e32 v77, v10
	s_nop 0
	v_add_f32_e32 v10, v70, v77
	v_add_f32_e32 v9, v10, v9
	v_sub_f32_e32 v10, v71, v172
	v_exp_f32_e32 v71, v10
	v_sub_f32_e32 v10, v69, v172
	v_exp_f32_e32 v69, v10
	s_nop 0
	v_add_f32_e32 v10, v71, v69
	v_add_f32_e32 v9, v10, v9
	v_sub_f32_e32 v10, v58, v172
	v_exp_f32_e32 v58, v10
	v_sub_f32_e32 v10, v56, v172
	v_exp_f32_e32 v56, v10
	s_nop 0
	v_add_f32_e32 v10, v58, v56
	v_add_f32_e32 v9, v10, v9
	v_sub_f32_e32 v10, v59, v172
	v_exp_f32_e32 v59, v10
	v_sub_f32_e32 v10, v57, v172
	v_exp_f32_e32 v68, v10
	s_nop 0
	v_add_f32_e32 v10, v59, v68
	v_add_f32_e32 v9, v10, v9
	v_sub_f32_e32 v10, v62, v172
	v_exp_f32_e32 v62, v10
	v_sub_f32_e32 v10, v60, v172
	v_exp_f32_e32 v60, v10
	s_nop 0
	v_add_f32_e32 v10, v62, v60
	v_add_f32_e32 v9, v10, v9
	v_sub_f32_e32 v10, v63, v172
	v_exp_f32_e32 v63, v10
	v_sub_f32_e32 v10, v61, v172
	v_exp_f32_e32 v61, v10
	s_nop 0
	v_add_f32_e32 v10, v63, v61
	v_add_f32_e32 v9, v10, v9
	v_sub_f32_e32 v10, v150, v172
	v_exp_f32_e32 v57, v10
	v_sub_f32_e32 v10, v55, v172
	v_exp_f32_e32 v55, v10
	s_nop 0
	v_add_f32_e32 v10, v57, v55
	v_add_f32_e32 v9, v10, v9
	v_sub_f32_e32 v10, v54, v172
	v_exp_f32_e32 v54, v10
	v_sub_f32_e32 v10, v53, v172
	v_exp_f32_e32 v53, v10
	s_nop 0
	v_add_f32_e32 v10, v54, v53
	v_add_f32_e32 v9, v10, v9
	v_sub_f32_e32 v10, v52, v172
	v_exp_f32_e32 v52, v10
	v_sub_f32_e32 v10, v50, v172
	v_exp_f32_e32 v50, v10
	s_nop 0
	v_add_f32_e32 v10, v52, v50
	v_add_f32_e32 v9, v10, v9
	v_sub_f32_e32 v10, v49, v172
	v_exp_f32_e32 v49, v10
	v_sub_f32_e32 v10, v48, v172
	v_exp_f32_e32 v48, v10
	s_nop 0
	v_add_f32_e32 v10, v49, v48
	v_add_f32_e32 v9, v10, v9
	v_sub_f32_e32 v10, v42, v172
	v_exp_f32_e32 v42, v10
	v_sub_f32_e32 v10, v40, v172
	v_exp_f32_e32 v40, v10
	s_nop 0
	v_add_f32_e32 v10, v42, v40
	v_add_f32_e32 v9, v10, v9
	v_sub_f32_e32 v10, v43, v172
	v_exp_f32_e32 v43, v10
	v_sub_f32_e32 v10, v41, v172
	v_exp_f32_e32 v41, v10
	s_nop 0
	v_add_f32_e32 v10, v43, v41
	v_add_f32_e32 v9, v10, v9
	v_sub_f32_e32 v10, v46, v172
	v_exp_f32_e32 v46, v10
	v_sub_f32_e32 v10, v44, v172
	v_exp_f32_e32 v44, v10
	s_nop 0
	v_add_f32_e32 v10, v46, v44
	v_add_f32_e32 v9, v10, v9
	v_sub_f32_e32 v10, v47, v172
	v_exp_f32_e32 v47, v10
	v_sub_f32_e32 v10, v45, v172
	v_exp_f32_e32 v45, v10
	s_nop 0
	v_add_f32_e32 v10, v47, v45
	v_add_f32_e32 v9, v10, v9
	v_sub_f32_e32 v10, v34, v172
	v_exp_f32_e32 v34, v10
	v_sub_f32_e32 v10, v32, v172
	v_exp_f32_e32 v32, v10
	s_nop 0
	v_add_f32_e32 v10, v34, v32
	v_add_f32_e32 v9, v10, v9
	v_sub_f32_e32 v10, v35, v172
	v_exp_f32_e32 v35, v10
	v_sub_f32_e32 v10, v33, v172
	v_exp_f32_e32 v33, v10
	s_nop 0
	v_add_f32_e32 v10, v35, v33
	v_add_f32_e32 v9, v10, v9
	v_sub_f32_e32 v10, v38, v172
	v_exp_f32_e32 v38, v10
	v_sub_f32_e32 v10, v36, v172
	v_exp_f32_e32 v36, v10
	s_nop 0
	v_add_f32_e32 v10, v38, v36
	v_add_f32_e32 v9, v10, v9
	v_sub_f32_e32 v10, v39, v172
	v_exp_f32_e32 v39, v10
	v_sub_f32_e32 v10, v37, v172
	v_exp_f32_e32 v37, v10
	s_nop 0
	v_add_f32_e32 v10, v39, v37
	v_add_f32_e32 v9, v10, v9
	v_sub_f32_e32 v10, v26, v172
	v_exp_f32_e32 v17, v10
	v_sub_f32_e32 v10, v24, v172
	v_exp_f32_e32 v19, v10
	v_sub_f32_e32 v10, v27, v172
	v_exp_f32_e32 v16, v10
	v_sub_f32_e32 v10, v25, v172
	v_exp_f32_e32 v18, v10
	s_nop 0
	v_pk_add_f32 v[10:11], v[16:17], v[18:19]
	s_nop 0
	v_add_f32_e32 v9, v11, v9
	v_add_f32_e32 v9, v10, v9
	v_sub_f32_e32 v10, v30, v172
	v_exp_f32_e32 v21, v10
	v_sub_f32_e32 v10, v28, v172
	v_exp_f32_e32 v23, v10
	v_sub_f32_e32 v10, v31, v172
	v_exp_f32_e32 v20, v10
	v_sub_f32_e32 v10, v29, v172
	v_exp_f32_e32 v22, v10
	v_cvt_pk_bf16_f32 v28, v81, v83
	v_cvt_pk_bf16_f32 v29, v145, v147
	v_cvt_pk_bf16_f32 v30, v82, v144
	v_cvt_pk_bf16_f32 v31, v146, v148
	s_nop 1
	s_nop 0
	v_pk_add_f32 v[10:11], v[20:21], v[22:23]
	s_nop 0
	v_add_f32_e32 v9, v11, v9
	v_add_f32_e32 v15, v10, v9
	v_sub_f32_e32 v9, v12, v172
	v_exp_f32_e32 v11, v8
	v_sub_f32_e32 v8, v13, v172
	v_sub_f32_e32 v10, v149, v172
	v_exp_f32_e32 v9, v9
	v_exp_f32_e32 v8, v8
	v_exp_f32_e32 v10, v10
	s_nop 0
	v_pk_add_f32 v[12:13], v[8:9], v[10:11]
	s_nop 0
	v_add_f32_e32 v13, v13, v15
	v_add_f32_e32 v26, v12, v13
	v_sub_f32_e32 v12, v14, v172
	v_exp_f32_e32 v13, v12
	v_sub_f32_e32 v12, v151, v172
	v_exp_f32_e32 v15, v12
	v_sub_f32_e32 v12, v152, v172
	v_sub_f32_e32 v14, v173, v172
	v_exp_f32_e32 v12, v12
	v_exp_f32_e32 v14, v14
	s_nop 0
	v_pk_add_f32 v[24:25], v[12:13], v[14:15]
	s_nop 0
	v_add_f32_e32 v25, v25, v26
	v_add_f32_e32 v24, v24, v25
	ds_bpermute_b32 v25, v114, v24
	v_lshl_add_u32 v26, v80, 1, v118
	ds_read_b128 v[80:83], v26 offset:55296
	s_waitcnt lgkmcnt(1)
	v_add_f32_e32 v24, v24, v25
	ds_bpermute_b32 v25, v117, v24
	s_waitcnt lgkmcnt(0)
	v_add_f32_e32 v24, v24, v25
	v_sub_f32_e32 v25, v143, v172
	v_exp_f32_e32 v25, v25
	s_nop 0
	v_add_f32_e32 v24, v25, v24
	v_add_u32_e32 v25, 0xd800, v26
	ds_read_b128 v[144:147], v25 offset:12544
	ds_read_b128 v[172:175], v25 offset:37632
	ds_read_b128 v[148:151], v25 offset:25088
	v_mfma_f32_16x16x32_bf16 v[80:83], v[80:83], v[28:31], 0
	s_waitcnt lgkmcnt(2)
	v_mfma_f32_16x16x32_bf16 v[144:147], v[144:147], v[28:31], 0
	s_waitcnt lgkmcnt(0)
	v_mfma_f32_16x16x32_bf16 v[148:151], v[148:151], v[28:31], 0
	v_mfma_f32_16x16x32_bf16 v[28:31], v[172:175], v[28:31], 0
	v_cvt_pk_bf16_f32 v172, v51, v74
	v_cvt_pk_bf16_f32 v173, v75, v78
	v_cvt_pk_bf16_f32 v174, v72, v73
	v_cvt_pk_bf16_f32 v175, v76, v79
	s_nop 1
	ds_read_b128 v[72:75], v26 offset:55360
	s_waitcnt lgkmcnt(0)
	v_mfma_f32_16x16x32_bf16 v[72:75], v[72:75], v[172:175], v[80:83]
	s_nop 2
	ds_read_b128 v[78:81], v25 offset:12608
	s_waitcnt lgkmcnt(0)
	v_mfma_f32_16x16x32_bf16 v[78:81], v[78:81], v[172:175], v[144:147]
	s_nop 2
	ds_read_b128 v[144:147], v25 offset:25152
	s_waitcnt lgkmcnt(0)
	v_mfma_f32_16x16x32_bf16 v[144:147], v[144:147], v[172:175], v[148:151]
	s_nop 2
	ds_read_b128 v[148:151], v25 offset:37696
	s_waitcnt lgkmcnt(0)
	v_mfma_f32_16x16x32_bf16 v[28:31], v[148:151], v[172:175], v[28:31]
	v_cvt_pk_bf16_f32 v148, v66, v67
	v_cvt_pk_bf16_f32 v149, v70, v71
	v_cvt_pk_bf16_f32 v150, v64, v65
	v_cvt_pk_bf16_f32 v151, v77, v69
	s_nop 1
	ds_read_b128 v[64:67], v26 offset:55424
	s_waitcnt lgkmcnt(0)
	v_mfma_f32_16x16x32_bf16 v[64:67], v[64:67], v[148:151], v[72:75]
	s_nop 2
	ds_read_b128 v[70:73], v25 offset:12672
	ds_read_b128 v[74:77], v25 offset:25216
	s_waitcnt lgkmcnt(1)
	v_mfma_f32_16x16x32_bf16 v[70:73], v[70:73], v[148:151], v[78:81]
	s_nop 2
	ds_read_b128 v[78:81], v25 offset:37760
	s_waitcnt lgkmcnt(0)
	v_mfma_f32_16x16x32_bf16 v[28:31], v[78:81], v[148:151], v[28:31]
	v_cvt_pk_bf16_f32 v78, v58, v59
	v_cvt_pk_bf16_f32 v79, v62, v63
	v_cvt_pk_bf16_f32 v80, v56, v68
	v_cvt_pk_bf16_f32 v81, v60, v61
	s_nop 1
	ds_read_b128 v[58:61], v26 offset:55488
	s_waitcnt lgkmcnt(0)
	v_mfma_f32_16x16x32_bf16 v[58:61], v[58:61], v[78:81], v[64:67]
	s_nop 2
	ds_read_b128 v[62:65], v25 offset:12736
	ds_read_b128 v[66:69], v25 offset:25280
	s_waitcnt lgkmcnt(1)
	v_mfma_f32_16x16x32_bf16 v[62:65], v[62:65], v[78:81], v[70:73]
	s_nop 2
	ds_read_b128 v[70:73], v25 offset:37824
	s_waitcnt lgkmcnt(0)
	v_mfma_f32_16x16x32_bf16 v[28:31], v[70:73], v[78:81], v[28:31]
	v_cvt_pk_bf16_f32 v70, v57, v54
	v_cvt_pk_bf16_f32 v71, v52, v49
	v_cvt_pk_bf16_f32 v72, v55, v53
	v_cvt_pk_bf16_f32 v73, v50, v48
	s_nop 1
	ds_read_b128 v[48:51], v26 offset:55552
	ds_read_b128 v[52:55], v25 offset:12800
	s_waitcnt lgkmcnt(1)
	v_mfma_f32_16x16x32_bf16 v[48:51], v[48:51], v[70:73], v[58:61]
	s_nop 2
	ds_read_b128 v[56:59], v25 offset:25344
	s_waitcnt lgkmcnt(1)
	v_mfma_f32_16x16x32_bf16 v[52:55], v[52:55], v[70:73], v[62:65]
	s_nop 2
	ds_read_b128 v[60:63], v25 offset:37888
	s_waitcnt lgkmcnt(0)
	v_mfma_f32_16x16x32_bf16 v[28:31], v[60:63], v[70:73], v[28:31]
	v_cvt_pk_bf16_f32 v60, v42, v43
	v_cvt_pk_bf16_f32 v61, v46, v47
	v_cvt_pk_bf16_f32 v62, v40, v41
	v_cvt_pk_bf16_f32 v63, v44, v45
	s_nop 1
	ds_read_b128 v[40:43], v26 offset:55616
	ds_read_b128 v[44:47], v25 offset:12864
	s_waitcnt lgkmcnt(1)
	v_mfma_f32_16x16x32_bf16 v[40:43], v[40:43], v[60:63], v[48:51]
	s_nop 2
	ds_read_b128 v[48:51], v25 offset:25408
	s_waitcnt lgkmcnt(1)
	v_mfma_f32_16x16x32_bf16 v[44:47], v[44:47], v[60:63], v[52:55]
	s_nop 2
	ds_read_b128 v[52:55], v25 offset:37952
	s_waitcnt lgkmcnt(0)
	v_mfma_f32_16x16x32_bf16 v[28:31], v[52:55], v[60:63], v[28:31]
	v_cvt_pk_bf16_f32 v52, v34, v35
	v_cvt_pk_bf16_f32 v53, v38, v39
	v_cvt_pk_bf16_f32 v54, v32, v33
	v_cvt_pk_bf16_f32 v55, v36, v37
	s_nop 1
	ds_read_b128 v[32:35], v26 offset:55680
	ds_read_b128 v[36:39], v25 offset:12928
	s_waitcnt lgkmcnt(1)
	v_mfma_f32_16x16x32_bf16 v[32:35], v[32:35], v[52:55], v[40:43]
	s_nop 2
	ds_read_b128 v[40:43], v25 offset:25472
	s_waitcnt lgkmcnt(1)
	v_mfma_f32_16x16x32_bf16 v[36:39], v[36:39], v[52:55], v[44:47]
	s_nop 2
	ds_read_b128 v[44:47], v25 offset:38016
	s_waitcnt lgkmcnt(0)
	v_mfma_f32_16x16x32_bf16 v[28:31], v[44:47], v[52:55], v[28:31]
	v_cvt_pk_bf16_f32 v44, v17, v16
	v_cvt_pk_bf16_f32 v45, v21, v20
	v_cvt_pk_bf16_f32 v46, v19, v18
	v_cvt_pk_bf16_f32 v47, v23, v22
	s_nop 1
	ds_read_b128 v[16:19], v26 offset:55744
	ds_read_b128 v[20:23], v25 offset:12992
	s_waitcnt lgkmcnt(1)
	v_mfma_f32_16x16x32_bf16 v[16:19], v[16:19], v[44:47], v[32:35]
	s_nop 2
	ds_read_b128 v[32:35], v25 offset:25536
	s_waitcnt lgkmcnt(1)
	v_mfma_f32_16x16x32_bf16 v[20:23], v[20:23], v[44:47], v[36:39]
	s_nop 2
	ds_read_b128 v[36:39], v25 offset:38080
	s_waitcnt lgkmcnt(0)
	v_mfma_f32_16x16x32_bf16 v[28:31], v[36:39], v[44:47], v[28:31]
	v_cvt_pk_bf16_f32 v36, v9, v8
	v_cvt_pk_bf16_f32 v37, v13, v12
	v_cvt_pk_bf16_f32 v38, v11, v10
	v_cvt_pk_bf16_f32 v39, v15, v14
	s_nop 1
	ds_read_b128 v[8:11], v26 offset:55808
	ds_read_b128 v[12:15], v25 offset:13056
	s_waitcnt lgkmcnt(1)
	v_mfma_f32_16x16x32_bf16 v[8:11], v[8:11], v[36:39], v[16:19]
	s_nop 2
	ds_read_b128 v[16:19], v25 offset:25600
	s_waitcnt lgkmcnt(1)
	v_mfma_f32_16x16x32_bf16 v[12:15], v[12:15], v[36:39], v[20:23]
	s_nop 2
	ds_read_b128 v[20:23], v25 offset:38144
	v_div_scale_f32 v25, s[0:1], v24, v24, 1.0
	v_mfma_f32_16x16x32_bf16 v[74:77], v[74:77], v[148:151], v[144:147]
	v_rcp_f32_e32 v26, v25
	s_mov_b32 s0, 0x1b400000
	v_fma_f32 v27, -v25, v26, 1.0
	v_mfma_f32_16x16x32_bf16 v[66:69], v[66:69], v[78:81], v[74:77]
	v_fmac_f32_e32 v26, v27, v26
	v_div_scale_f32 v27, vcc, 1.0, v24, 1.0
	s_waitcnt lgkmcnt(0)
	v_mfma_f32_16x16x32_bf16 v[20:23], v[20:23], v[36:39], v[28:31]
	s_nop 2
	v_mul_f32_e32 v28, v27, v26
	v_fma_f32 v29, -v25, v28, v27
	v_mfma_f32_16x16x32_bf16 v[56:59], v[56:59], v[70:73], v[66:69]
	v_fmac_f32_e32 v28, v29, v26
	v_fma_f32 v25, -v25, v28, v27
	v_div_fmas_f32 v25, v25, v26, v28
	v_div_fixup_f32 v24, v25, v24, 1.0
	v_mfma_f32_16x16x32_bf16 v[48:51], v[48:51], v[60:63], v[56:59]
	v_mul_f32_e64 v8, v24, v8
	v_mul_f32_e64 v9, v24, v9
	v_pk_mul_f32 v[10:11], v[24:25], v[10:11] op_sel_hi:[0,1]
	v_cvt_pk_bf16_f32 v8, v8, v9
	s_nop 3
	v_mfma_f32_16x16x32_bf16 v[40:43], v[40:43], v[52:55], v[48:51]
	v_cvt_pk_bf16_f32 v9, v10, v11
	v_lshl_add_u64 v[26:27], v[110:111], 0, s[16:17]
	v_add_co_u32_e32 v10, vcc, s0, v26
	s_nop 5
	v_mfma_f32_16x16x32_bf16 v[32:35], v[32:35], v[44:47], v[40:43]
	s_nop 0
	v_addc_co_u32_e32 v11, vcc, 0, v27, vcc
	v_pk_mul_f32 v[12:13], v[24:25], v[12:13] op_sel_hi:[0,1]
	global_store_dwordx2 v[10:11], v[8:9], off
	v_pk_mul_f32 v[8:9], v[24:25], v[14:15] op_sel_hi:[0,1]
	v_cvt_pk_bf16_f32 v12, v12, v13
	s_nop 3
	v_mfma_f32_16x16x32_bf16 v[16:19], v[16:19], v[36:39], v[32:35]
	v_cvt_pk_bf16_f32 v13, v8, v9
	global_store_dwordx2 v[10:11], v[12:13], off offset:32
	s_nop 5
	v_pk_mul_f32 v[12:13], v[24:25], v[16:17] op_sel_hi:[0,1]
	v_cvt_pk_bf16_f32 v12, v12, v13
	v_pk_mul_f32 v[8:9], v[24:25], v[18:19] op_sel_hi:[0,1]
	v_cvt_pk_bf16_f32 v13, v8, v9
	global_store_dwordx2 v[10:11], v[12:13], off offset:64
	v_pk_mul_f32 v[12:13], v[24:25], v[20:21] op_sel_hi:[0,1]
	v_cvt_pk_bf16_f32 v12, v12, v13
	v_pk_mul_f32 v[8:9], v[24:25], v[22:23] op_sel_hi:[0,1]
	v_cvt_pk_bf16_f32 v13, v8, v9
	s_add_u32 s16, s16, 0x4000
	global_store_dwordx2 v[10:11], v[12:13], off offset:96
	s_addc_u32 s17, s17, 0
	s_add_i32 s18, s18, 0xd000
	s_add_i32 s19, s19, 16
	s_mov_b64 s[0:1], 0x400
	s_waitcnt vmcnt(4)
	v_mov_b64_e32 v[10:11], v[6:7]
	v_lshl_add_u64 v[108:109], v[108:109], 0, s[0:1]
	s_cmp_eq_u32 s16, 0x10000
	v_mov_b64_e32 v[8:9], v[4:5]
	s_cbranch_scc1 .LBB0_564
.LBB0_579:
	s_cmpk_lg_u32 s16, 0xc000
	s_cselect_b32 s8, s18, 0x27000
	v_mov_b64_e32 v[82:83], v[2:3]
	v_lshl_add_u64 v[4:5], s[8:9], 1, v[106:107]
	v_mov_b64_e32 v[80:81], v[0:1]
	global_load_dwordx4 v[0:3], v[4:5], off
	s_nop 0
	global_load_dwordx4 v[4:7], v[4:5], off offset:64
	v_lshlrev_b32_e32 v13, 16, v81
	v_lshlrev_b32_e32 v12, 16, v80
	v_and_b32_e32 v15, 0xffff0000, v81
	v_and_b32_e32 v14, 0xffff0000, v80
	v_and_b32_e32 v17, 0xffff0000, v82
	v_lshlrev_b32_e32 v16, 16, v82
	v_and_b32_e32 v19, 0xffff0000, v83
	v_lshlrev_b32_e32 v18, 16, v83
	ds_bpermute_b32 v26, v114, v12
	ds_bpermute_b32 v24, v114, v14
	ds_bpermute_b32 v27, v114, v13
	ds_bpermute_b32 v25, v114, v15
	ds_bpermute_b32 v22, v114, v16
	ds_bpermute_b32 v23, v114, v17
	ds_bpermute_b32 v20, v114, v18
	ds_bpermute_b32 v21, v114, v19
	s_and_saveexec_b64 s[0:1], s[48:49]
	s_cbranch_execz .LBB0_581
	v_mov_b32_e32 v28, v176
	v_mov_b32_e32 v29, v177
	v_mov_b32_e32 v30, v178
	v_mov_b32_e32 v31, v179
	v_mov_b32_e32 v32, v180
	v_mov_b32_e32 v33, v181
	v_mov_b32_e32 v34, v182
	v_mov_b32_e32 v35, v183
	v_mov_b32_e32 v36, v184
	v_mov_b32_e32 v37, v185
	v_mov_b32_e32 v38, v186
	v_mov_b32_e32 v39, v187
	v_mov_b32_e32 v40, v188
	v_mov_b32_e32 v41, v189
	v_mov_b32_e32 v42, v190
	v_mov_b32_e32 v43, v191
	global_load_dwordx4 v[176:179], v[108:109], off offset:1024
	global_load_dwordx4 v[180:183], v[108:109], off offset:1056
	global_load_dwordx4 v[184:187], v[108:109], off offset:1072
	global_load_dwordx4 v[188:191], v[108:109], off offset:1040
	s_waitcnt lgkmcnt(4)
	v_pk_mul_f32 v[24:25], v[90:91], v[24:25]
	s_waitcnt lgkmcnt(2)
	v_pk_mul_f32 v[22:23], v[90:91], v[22:23]
	s_waitcnt lgkmcnt(0)
	v_pk_mul_f32 v[20:21], v[90:91], v[20:21]
	v_pk_mul_f32 v[26:27], v[90:91], v[26:27]
	v_mov_b32_e32 v45, v30
	v_mov_b32_e32 v47, v34
	v_mov_b32_e32 v34, v33
	v_mov_b32_e32 v46, v32
	v_mov_b32_e32 v30, v29
	v_pk_mul_f32 v[22:23], v[22:23], v[36:37]
	v_pk_mul_f32 v[20:21], v[20:21], v[38:39]
	v_pk_mul_f32 v[24:25], v[24:25], v[34:35]
	v_mov_b32_e32 v44, v28
	v_pk_mul_f32 v[26:27], v[26:27], v[46:47]
	v_pk_fma_f32 v[16:17], v[40:41], v[16:17], v[22:23]
	v_pk_fma_f32 v[18:19], v[42:43], v[18:19], v[20:21]
	v_pk_fma_f32 v[14:15], v[30:31], v[14:15], v[24:25]
	v_pk_fma_f32 v[12:13], v[44:45], v[12:13], v[26:27]
	v_cvt_pk_bf16_f32 v82, v16, v17
	v_cvt_pk_bf16_f32 v81, v13, v15
	v_cvt_pk_bf16_f32 v80, v12, v14
	v_cvt_pk_bf16_f32 v83, v18, v19
